# v12 + grid barrier: globally-last XCD leader bumps every XCD generation flag directly (no TOPGEN hop), other leaders wait on their own flag
# speedup vs baseline: 1.0132x; 1.0026x over previous
; __device__ __forceinline__ unsigned xb_ld(unsigned* p)              { return __hip_atomic_load(p, __ATOMIC_RELAXED, __HIP_MEMORY_SCOPE_AGENT); }
; __device__ __forceinline__ unsigned xb_add(unsigned* p, unsigned v) { return __hip_atomic_fetch_add(p, v, __ATOMIC_RELAXED, __HIP_MEMORY_SCOPE_AGENT); }
; #define XB_SPIN(cond, bar) do { unsigned _sp = 0; while (cond) { __builtin_amdgcn_s_sleep(1); \
;     if ((++_sp & 255u) == 0u) { if (xb_ld(&(bar)[XB_TMO])) break; if (_sp > XB_SPIN_CAP) { atomicAdd(&(bar)[XB_TMO], 1u); break; } } } } while (0)
; __device__ __forceinline__ void xcd_barrier(const XcdBarrier& b, int wave) {
;     ...
;         const unsigned old = xb_add(&bar[XB_XSUB(b.x)], 1u);
;         const unsigned gen = old / nloc;
;         if (old + 1u == (gen + 1u) * nloc) {
;             __builtin_amdgcn_fence(__ATOMIC_RELEASE, "agent");
;             asm volatile("s_waitcnt vmcnt(0)" ::: "memory");
;             const unsigned og = xb_add(&bar[XB_TOP], 1u);
;             const unsigned tg = og / nx;
;             if (og + 1u == (tg + 1u) * nx) xb_add(&bar[XB_TOPGEN], 1u);
;             else XB_SPIN(xb_ld(&bar[XB_TOPGEN]) == tg, bar);
;             __builtin_amdgcn_fence(__ATOMIC_ACQUIRE, "agent");
;             xb_add(&bar[XB_XGEN(b.x)], 1u);
;             asm volatile("s_waitcnt vmcnt(0)" ::: "memory");
;         } else {
;             XB_SPIN(xb_ld(&bar[XB_XGEN(b.x)]) == gen, bar);
;             __builtin_amdgcn_fence(__ATOMIC_ACQUIRE, "agent");
;             asm volatile("s_waitcnt vmcnt(0)" ::: "memory");
;         }
.LBB0_1085:
	s_andn2_saveexec_b64 s[0:1], s[22:23]
	s_cbranch_execz .LBB0_1103
	s_mov_b64 s[0:1], exec
	v_mov_b32_e32 v7, v0
	buffer_wbl2 sc1
	s_waitcnt lgkmcnt(0)
	s_waitcnt vmcnt(0)
	v_mbcnt_lo_u32_b32 v0, s0, 0
	v_mbcnt_hi_u32_b32 v0, s1, v0
	v_cmp_eq_u32_e32 vcc, 0, v0
	s_and_saveexec_b64 s[22:23], vcc
	s_cbranch_execz .LBB0_1088
	s_bcnt1_i32_b64 s0, s[0:1]
	v_mov_b32_e32 v3, s0
	v_readlane_b32 s0, v253, 55
	v_readlane_b32 s1, v253, 56
	s_nop 4
	global_atomic_add v3, v1, v3, s[0:1] sc0
.LBB0_1088:
	s_or_b64 exec, exec, s[22:23]
	s_waitcnt vmcnt(0)
	v_readfirstlane_b32 s0, v3
	v_sub_u32_e32 v4, 0, v2
	v_readlane_b32 s2, v253, 57
	v_add_u32_e32 v3, s0, v0
	v_cvt_f32_u32_e32 v0, v2
	v_readlane_b32 s3, v253, 58
	s_mov_b64 s[0:1], -1
	v_rcp_iflag_f32_e32 v0, v0
	s_nop 0
	v_mul_f32_e32 v0, 0x4f7ffffe, v0
	v_cvt_u32_f32_e32 v0, v0
	v_mul_lo_u32 v4, v4, v0
	v_mul_hi_u32 v4, v0, v4
	v_add_u32_e32 v0, v0, v4
	v_mul_hi_u32 v0, v3, v0
	v_mul_lo_u32 v4, v0, v2
	v_sub_u32_e32 v4, v3, v4
	v_cmp_ge_u32_e32 vcc, v4, v2
	v_add_u32_e32 v5, 1, v0
	v_add_u32_e32 v3, 1, v3
	v_cndmask_b32_e32 v0, v0, v5, vcc
	v_sub_u32_e32 v5, v4, v2
	v_cndmask_b32_e32 v4, v4, v5, vcc
	v_cmp_ge_u32_e32 vcc, v4, v2
	v_add_u32_e32 v4, 1, v0
	s_nop 0
	v_cndmask_b32_e32 v0, v0, v4, vcc
	v_mul_lo_u32 v4, v2, v0
	v_add_u32_e32 v2, v4, v2
	v_cmp_ne_u32_e32 vcc, v3, v2
	v_mov_b64_e32 v[2:3], s[2:3]
	s_and_saveexec_b64 s[22:23], vcc
	s_cbranch_execz .LBB0_1100
	v_readlane_b32 s0, v253, 53
	v_readlane_b32 s1, v253, 54
	s_nop 4
	global_load_dword v2, v1, s[0:1] sc1
	s_mov_b64 s[0:1], 0
	s_waitcnt vmcnt(0)
	v_cmp_eq_u32_e32 vcc, v2, v7
	s_and_saveexec_b64 s[24:25], vcc
	s_cbranch_execz .LBB0_1099
	s_mov_b32 s2, 1
	s_branch .LBB0_1092

; __device__ __forceinline__ unsigned xb_ld(unsigned* p)              { return __hip_atomic_load(p, __ATOMIC_RELAXED, __HIP_MEMORY_SCOPE_AGENT); }
; #define XB_SPIN(cond, bar) do { unsigned _sp = 0; while (cond) { __builtin_amdgcn_s_sleep(1); \
;     if ((++_sp & 255u) == 0u) { if (xb_ld(&(bar)[XB_TMO])) break; if (_sp > XB_SPIN_CAP) { atomicAdd(&(bar)[XB_TMO], 1u); break; } } } } while (0)
; __device__ __forceinline__ void xcd_barrier(const XcdBarrier& b, int wave) {
;     ...
;             else XB_SPIN(xb_ld(&bar[XB_TOPGEN]) == tg, bar);
.LBB0_1096:
	v_readlane_b32 s4, v253, 53
	v_readlane_b32 s5, v253, 54
	s_add_i32 s2, s2, 1
	s_mov_b64 s[38:39], -1
	s_nop 2
	global_load_dword v2, v1, s[4:5] sc1
	s_waitcnt vmcnt(0)
	v_cmp_ne_u32_e32 vcc, v2, v7
	s_orn2_b64 s[36:37], vcc, exec
	s_branch .LBB0_1091

; __device__ __forceinline__ unsigned xb_ld(unsigned* p)              { return __hip_atomic_load(p, __ATOMIC_RELAXED, __HIP_MEMORY_SCOPE_AGENT); }
; __device__ __forceinline__ unsigned xb_add(unsigned* p, unsigned v) { return __hip_atomic_fetch_add(p, v, __ATOMIC_RELAXED, __HIP_MEMORY_SCOPE_AGENT); }
; #define XB_SPIN(cond, bar) do { unsigned _sp = 0; while (cond) { __builtin_amdgcn_s_sleep(1); \
;     if ((++_sp & 255u) == 0u) { if (xb_ld(&(bar)[XB_TMO])) break; if (_sp > XB_SPIN_CAP) { atomicAdd(&(bar)[XB_TMO], 1u); break; } } } } while (0)
; __device__ __forceinline__ void xcd_barrier(const XcdBarrier& b, int wave) {
;     ...
;             const unsigned og = xb_add(&bar[XB_TOP], 1u);
;             const unsigned tg = og / nx;
;             if (og + 1u == (tg + 1u) * nx) xb_add(&bar[XB_TOPGEN], 1u);
;             else XB_SPIN(xb_ld(&bar[XB_TOPGEN]) == tg, bar);
;             __builtin_amdgcn_fence(__ATOMIC_ACQUIRE, "agent");
;             xb_add(&bar[XB_XGEN(b.x)], 1u);
;             asm volatile("s_waitcnt vmcnt(0)" ::: "memory");
;         } else {
;             XB_SPIN(xb_ld(&bar[XB_XGEN(b.x)]) == gen, bar);
;             __builtin_amdgcn_fence(__ATOMIC_ACQUIRE, "agent");
;             asm volatile("s_waitcnt vmcnt(0)" ::: "memory");
;         }
.LBB0_1100:
	s_or_b64 exec, exec, s[22:23]
	s_and_saveexec_b64 s[22:23], s[0:1]
	s_cbranch_execz .LBB0_1102
	global_atomic_add v[2:3], v224, off
	v_readlane_b32 s0, v252, 51
	v_readlane_b32 s1, v252, 52
	v_mov_b32_e32 v4, 0x2000
	s_nop 4
	global_atomic_add v4, v224, s[0:1]
	global_atomic_add v4, v224, s[0:1] offset:256
	global_atomic_add v4, v224, s[0:1] offset:512
	global_atomic_add v4, v224, s[0:1] offset:768
	global_atomic_add v4, v224, s[0:1] offset:1024
	global_atomic_add v4, v224, s[0:1] offset:1280
	global_atomic_add v4, v224, s[0:1] offset:1536
	global_atomic_add v4, v224, s[0:1] offset:1792
	global_atomic_add v4, v224, s[0:1] offset:2048
	global_atomic_add v4, v224, s[0:1] offset:2304
	global_atomic_add v4, v224, s[0:1] offset:2560
	global_atomic_add v4, v224, s[0:1] offset:2816
	global_atomic_add v4, v224, s[0:1] offset:3072
	global_atomic_add v4, v224, s[0:1] offset:3328
	global_atomic_add v4, v224, s[0:1] offset:3584
	global_atomic_add v4, v224, s[0:1] offset:3840
.LBB0_1102:
	s_or_b64 exec, exec, s[22:23]
	v_readlane_b32 s0, v253, 53
	v_readlane_b32 s1, v253, 54
	s_waitcnt vmcnt(0)
	buffer_inv sc1
	s_nop 2
	s_waitcnt vmcnt(0)
